# plus redundant setprio pairs removed in attention loops
# speedup vs baseline: 1.0011x; 1.0011x over previous
; __device__ __forceinline__ void at_qk_half(const bool ONLINE, const bool act, const LAS unsigned char* kp, u32x4& pfa, u32x4& pfb, const char* pga, const char* pgb, const bf16x8 (&qf)[4], int q, int q0, int kbase, int hh, float& mrun, f32x16 (&O)[4], f32x16& L, bf16x8 (&pf)[4]) {
;     __builtin_amdgcn_s_setprio(3);
;     bf16x8 kf[8];
; #pragma unroll
;     for (int s = 0; s < 4; ++s) { kf[2 * s] = *(const LAS bf16x8*)(kp + 32 * s); kf[2 * s + 1] = *(const LAS bf16x8*)(kp + 32 * AT_ROWB + 32 * s); }
;     __builtin_amdgcn_sched_barrier(0);
;     pfa = *(const u32x4*)pga; pfb = *(const u32x4*)pgb;
;     __builtin_amdgcn_sched_barrier(0);
;     if (!act) { __builtin_amdgcn_s_setprio(0); return; }
;     f32x16 s0, s1;
; #pragma unroll
;     for (int i = 0; i < 16; ++i) { s0[i] = 0.f; s1[i] = 0.f; }
; #pragma unroll
;     for (int s = 0; s < 4; ++s) { s0 = MFMA32(kf[2 * s], qf[s], s0); s1 = MFMA32(kf[2 * s + 1], qf[s], s1); }
;     __builtin_amdgcn_s_setprio(0);
;     if (kbase + 63 > q0) {
;         const int kb = kbase + 4 * hh;
; #pragma unroll
;         for (int i = 0; i < 16; ++i) { const int kv = kb + (i & 3) + 8 * (i >> 2); if (kv > q) s0[i] = -INFINITY; if (kv + 32 > q) s1[i] = -INFINITY; }
;     }
;     if (ONLINE) {
; #pragma unroll
;         for (int i = 0; i < 16; ++i) { s0[i] -= mrun; s1[i] -= mrun; }
;         float mx = fmaxf(s0[0], s1[0]);
; #pragma unroll
;         for (int i = 1; i < 16; ++i) mx = at_max3(mx, s0[i], s1[i]);
;         mx = half_swap_max(mx);
;         if (__builtin_amdgcn_ballot_w64(mx > 8.f) != 0ull) {
;             const float d = fmaxf(mx, 0.f); const float alpha = __builtin_amdgcn_exp2f(-d); mrun += d;
; #pragma unroll
;             for (int e = 0; e < 4; ++e)
; #pragma unroll
;                 for (int i = 0; i < 16; ++i) O[e][i] *= alpha;
; __device__ __forceinline__ void attn_item(LAS unsigned char* lds, const bf16_t* Q, const bf16_t* Kb, const bf16_t* VT, bf16_t* aout, const float* subg, float lam, float omli, float kbound, int head, int qb) {
;     ...
;             __syncthreads();
;             __builtin_amdgcn_s_setprio(3);
;             { const int jc_ = (j + 2) < ntm1 ? (j + 2) : ntm1; const size_t ko_ = (size_t)jc_ * 8192; const char* pga = bK1 + ko_ + koff; const char* pgb = bK2 + ko_ + koff;
;               at_qk_half(online, kbase <= qmax, stg + kfo, ks0, ks1, pga, pgb, qf, q, q0, kbase, hh, mrun, O, L, pf); }
.Lmy_wj1:
	v_add_u32_e32 v232, s56, v212
	s_bitcmp1_b32 s45, 0
	s_cselect_b32 s53, 0x4800, 0
	s_sub_i32 s57, s1, 63
	s_waitcnt lgkmcnt(0)
	s_barrier
	s_setprio 3
	s_add_i32 s45, s45, 2
	s_min_i32 s58, s45, s41
	s_lshl_b64 s[54:55], s[58:59], 13
	v_lshl_add_u64 v[100:101], v[204:205], 0, s[54:55]
	v_lshl_add_u64 v[102:103], v[206:207], 0, s[54:55]
	s_cmp_gt_i32 s57, s40
	v_add_u32_e32 v104, s53, v230
	ds_read_b128 v[96:99], v104
	ds_read_b128 v[166:169], v104 offset:32
	ds_read_b128 v[162:165], v104 offset:64
	ds_read_b128 v[154:157], v104 offset:96
	ds_read_b128 v[178:181], v104 offset:4608
	ds_read_b128 v[170:173], v104 offset:4640
	ds_read_b128 v[174:177], v104 offset:4672
	ds_read_b128 v[158:161], v104 offset:4704
	global_load_dwordx4 v[142:145], v[100:101], off
	global_load_dwordx4 v[138:141], v[102:103], off
	s_cbranch_scc1 .LBB0_304
	s_cmp_le_i32 s1, s33
	s_cbranch_scc0 .Lmy_slow1
	s_andn2_b64 vcc, exec, s[64:65]
	s_cbranch_vccz .Lmy_slow1
	s_waitcnt lgkmcnt(7)
	v_mfma_f32_32x32x16_bf16 v[96:111], v[96:99], v[126:129], 0
	s_waitcnt lgkmcnt(6)
	v_mfma_f32_32x32x16_bf16 v[96:111], v[166:169], v[122:125], v[96:111]
	s_waitcnt lgkmcnt(5)
	v_mfma_f32_32x32x16_bf16 v[96:111], v[162:165], v[118:121], v[96:111]
	s_waitcnt lgkmcnt(4)
	v_mfma_f32_32x32x16_bf16 v[96:111], v[154:157], v[114:117], v[96:111]
	s_waitcnt lgkmcnt(3)
	v_mfma_f32_32x32x16_bf16 v[80:95], v[178:181], v[126:129], 0
	s_waitcnt lgkmcnt(2)
	v_mfma_f32_32x32x16_bf16 v[80:95], v[170:173], v[122:125], v[80:95]
	s_nop 8
	v_exp_f32_e32 v96, v96
	v_exp_f32_e32 v97, v97
	v_exp_f32_e32 v98, v98
	v_exp_f32_e32 v99, v99
	s_waitcnt lgkmcnt(1)
	v_mfma_f32_32x32x16_bf16 v[80:95], v[174:177], v[118:121], v[80:95]
	v_exp_f32_e32 v100, v100
	v_exp_f32_e32 v101, v101
	v_exp_f32_e32 v102, v102
	v_exp_f32_e32 v103, v103
	s_waitcnt lgkmcnt(0)
	v_mfma_f32_32x32x16_bf16 v[80:95], v[158:161], v[114:117], v[80:95]
	s_setprio 0
	v_exp_f32_e32 v104, v104
	v_exp_f32_e32 v105, v105
	v_exp_f32_e32 v106, v106
	v_exp_f32_e32 v107, v107
	v_exp_f32_e32 v108, v108
	v_exp_f32_e32 v109, v109
	v_exp_f32_e32 v110, v110
	v_exp_f32_e32 v111, v111
	s_nop 3
	v_exp_f32_e32 v154, v80
	v_exp_f32_e32 v155, v81
	v_exp_f32_e32 v156, v82
	v_exp_f32_e32 v157, v83
	v_exp_f32_e32 v158, v84
	v_exp_f32_e32 v159, v85
	v_exp_f32_e32 v160, v86
	v_exp_f32_e32 v161, v87
	v_exp_f32_e32 v162, v88
	v_exp_f32_e32 v163, v89
	v_exp_f32_e32 v164, v90
	v_exp_f32_e32 v165, v91
	v_exp_f32_e32 v166, v92
	v_exp_f32_e32 v167, v93
	v_exp_f32_e32 v168, v94
	v_exp_f32_e32 v169, v95
	v_cvt_pk_bf16_f32 v80, v96, v97
	v_cvt_pk_bf16_f32 v81, v98, v99
	v_cvt_pk_bf16_f32 v82, v100, v101
	v_cvt_pk_bf16_f32 v83, v102, v103
	v_cvt_pk_bf16_f32 v84, v154, v155
	v_cvt_pk_bf16_f32 v85, v156, v157
	v_cvt_pk_bf16_f32 v86, v158, v159
	v_cvt_pk_bf16_f32 v87, v160, v161
	v_cvt_pk_bf16_f32 v88, v104, v105
	v_cvt_pk_bf16_f32 v89, v106, v107
	v_cvt_pk_bf16_f32 v90, v108, v109
	v_cvt_pk_bf16_f32 v91, v110, v111
	v_cvt_pk_bf16_f32 v92, v162, v163
	v_cvt_pk_bf16_f32 v93, v164, v165
	v_cvt_pk_bf16_f32 v94, v166, v167
	v_cvt_pk_bf16_f32 v95, v168, v169
	s_branch .LBB0_304

; #define AT_WRITE_V(jn) do { LAS unsigned char* n_ = lds + ((jn) & 1) * AT_KST; *(LAS u32x4*)(n_ + dV0) = vs0; *(LAS u32x4*)(n_ + dV1) = vs1; } while (0)
; __device__ __forceinline__ void attn_item(LAS unsigned char* lds, const bf16_t* Q, const bf16_t* Kb, const bf16_t* VT, bf16_t* aout, const float* subg, float lam, float omli, float kbound, int head, int qb) {
;     ...
;             __builtin_amdgcn_s_setprio(3);
;             AT_WRITE_V(j + 1);
;             __syncthreads();
;             __builtin_amdgcn_s_setprio(0);
;         }
.LBB0_304:
	s_setprio 3
	s_waitcnt vmcnt(3)
	ds_write_b128 v232, v[146:149] offset:36864
	s_waitcnt vmcnt(2)
	ds_write_b128 v232, v[150:153] offset:46080
	s_waitcnt lgkmcnt(0)
	s_barrier
	s_setprio 0
	s_add_i32 s1, s1, 64
	s_cmp_eq_u32 s0, s44
	s_cbranch_scc1 .LBB0_307
	s_mov_b32 s45, s44
	s_branch .LBB0_295

; __device__ __forceinline__ void at_qk_half(const bool ONLINE, const bool act, const LAS unsigned char* kp, u32x4& pfa, u32x4& pfb, const char* pga, const char* pgb, const bf16x8 (&qf)[4], int q, int q0, int kbase, int hh, float& mrun, f32x16 (&O)[4], f32x16& L, bf16x8 (&pf)[4]) {
;     __builtin_amdgcn_s_setprio(3);
;     bf16x8 kf[8];
; #pragma unroll
;     for (int s = 0; s < 4; ++s) { kf[2 * s] = *(const LAS bf16x8*)(kp + 32 * s); kf[2 * s + 1] = *(const LAS bf16x8*)(kp + 32 * AT_ROWB + 32 * s); }
;     __builtin_amdgcn_sched_barrier(0);
;     pfa = *(const u32x4*)pga; pfb = *(const u32x4*)pgb;
;     __builtin_amdgcn_sched_barrier(0);
;     if (!act) { __builtin_amdgcn_s_setprio(0); return; }
;     f32x16 s0, s1;
; #pragma unroll
;     for (int i = 0; i < 16; ++i) { s0[i] = 0.f; s1[i] = 0.f; }
; #pragma unroll
;     for (int s = 0; s < 4; ++s) { s0 = MFMA32(kf[2 * s], qf[s], s0); s1 = MFMA32(kf[2 * s + 1], qf[s], s1); }
;     __builtin_amdgcn_s_setprio(0);
;     if (kbase + 63 > q0) {
;         const int kb = kbase + 4 * hh;
; #pragma unroll
;         for (int i = 0; i < 16; ++i) { const int kv = kb + (i & 3) + 8 * (i >> 2); if (kv > q) s0[i] = -INFINITY; if (kv + 32 > q) s1[i] = -INFINITY; }
;     }
;     if (ONLINE) {
; #pragma unroll
;         for (int i = 0; i < 16; ++i) { s0[i] -= mrun; s1[i] -= mrun; }
;         float mx = fmaxf(s0[0], s1[0]);
; #pragma unroll
;         for (int i = 1; i < 16; ++i) mx = at_max3(mx, s0[i], s1[i]);
;         mx = half_swap_max(mx);
;         if (__builtin_amdgcn_ballot_w64(mx > 8.f) != 0ull) {
;             const float d = fmaxf(mx, 0.f); const float alpha = __builtin_amdgcn_exp2f(-d); mrun += d;
; #pragma unroll
;             for (int e = 0; e < 4; ++e)
; __device__ __forceinline__ void attn_item(LAS unsigned char* lds, const bf16_t* Q, const bf16_t* Kb, const bf16_t* VT, bf16_t* aout, const float* subg, float lam, float omli, float kbound, int head, int qb) {
;     ...
;             const LAS unsigned char* stg = lds + (j & 1) * AT_KST; const int kbase = j * 64; const bool act = kbase <= qmax;
;             __builtin_amdgcn_s_setprio(3);
;             { const int jc_ = (j + 1) < ntm1 ? (j + 1) : ntm1; const size_t vo_ = (size_t)jc_ * 16384; const char* pga = bV0 + vo_ + voff; const char* pgb = bV1 + vo_ + voff;
;               at_qk_half(online, act, stg + kfo, vs0, vs1, pga, pgb, qf, q, q0, kbase, hh, mrun, O, L, pf); }
.LBB0_313:
	s_bitcmp1_b32 s53, 0
	s_cselect_b32 s0, 0x4800, 0
	s_add_i32 s54, s0, 0
	s_sub_i32 s55, s45, 63
	s_cmp_le_i32 s55, s40
	s_cselect_b64 s[0:1], -1, 0
	s_add_i32 s56, s53, 1
	s_min_i32 s58, s56, s41
	s_lshl_b64 s[60:61], s[58:59], 14
	s_cmp_gt_i32 s55, s40
	s_setprio 3
	v_lshl_add_u64 v[100:101], v[208:209], 0, s[60:61]
	v_lshl_add_u64 v[102:103], v[210:211], 0, s[60:61]
	v_add_u32_e32 v104, s54, v229
	ds_read_b128 v[96:99], v104
	ds_read_b128 v[158:161], v104 offset:32
	ds_read_b128 v[154:157], v104 offset:64
	ds_read_b128 v[146:149], v104 offset:96
	ds_read_b128 v[170:173], v104 offset:4608
	ds_read_b128 v[162:165], v104 offset:4640
	ds_read_b128 v[166:169], v104 offset:4672
	ds_read_b128 v[150:153], v104 offset:4704
	global_load_dwordx4 v[138:141], v[100:101], off
	global_load_dwordx4 v[142:145], v[102:103], off
	s_cbranch_scc1 .LBB0_320
	s_cmp_le_i32 s45, s33
	s_cbranch_scc0 .Lmy_slow2
	s_andn2_b64 vcc, exec, s[64:65]
	s_cbranch_vccz .Lmy_slow2
	s_waitcnt lgkmcnt(7)
	v_mfma_f32_32x32x16_bf16 v[96:111], v[96:99], v[126:129], 0
	s_waitcnt lgkmcnt(6)
	v_mfma_f32_32x32x16_bf16 v[96:111], v[158:161], v[122:125], v[96:111]
	s_waitcnt lgkmcnt(5)
	v_mfma_f32_32x32x16_bf16 v[96:111], v[154:157], v[118:121], v[96:111]
	s_waitcnt lgkmcnt(4)
	v_mfma_f32_32x32x16_bf16 v[96:111], v[146:149], v[114:117], v[96:111]
	s_waitcnt lgkmcnt(3)
	v_mfma_f32_32x32x16_bf16 v[80:95], v[170:173], v[126:129], 0
	s_waitcnt lgkmcnt(2)
	v_mfma_f32_32x32x16_bf16 v[80:95], v[162:165], v[122:125], v[80:95]
	s_nop 8
	v_exp_f32_e32 v96, v96
	v_exp_f32_e32 v97, v97
	v_exp_f32_e32 v98, v98
	v_exp_f32_e32 v99, v99
	s_waitcnt lgkmcnt(1)
	v_mfma_f32_32x32x16_bf16 v[80:95], v[166:169], v[118:121], v[80:95]
	v_exp_f32_e32 v100, v100
	v_exp_f32_e32 v101, v101
	v_exp_f32_e32 v102, v102
	v_exp_f32_e32 v103, v103
	s_waitcnt lgkmcnt(0)
	v_mfma_f32_32x32x16_bf16 v[80:95], v[150:153], v[114:117], v[80:95]
	s_setprio 0
	v_exp_f32_e32 v104, v104
	v_exp_f32_e32 v105, v105
	v_exp_f32_e32 v106, v106
	v_exp_f32_e32 v107, v107
	v_exp_f32_e32 v108, v108
	v_exp_f32_e32 v109, v109
	v_exp_f32_e32 v110, v110
	v_exp_f32_e32 v111, v111
	s_nop 3
	v_exp_f32_e32 v146, v80
	v_exp_f32_e32 v147, v81
	v_exp_f32_e32 v148, v82
	v_exp_f32_e32 v149, v83
	v_exp_f32_e32 v150, v84
	v_exp_f32_e32 v151, v85
	v_exp_f32_e32 v152, v86
	v_exp_f32_e32 v153, v87
	v_exp_f32_e32 v154, v88
	v_exp_f32_e32 v155, v89
	v_exp_f32_e32 v156, v90
	v_exp_f32_e32 v157, v91
	v_exp_f32_e32 v158, v92
	v_exp_f32_e32 v159, v93
	v_exp_f32_e32 v160, v94
	v_exp_f32_e32 v161, v95
	v_cvt_pk_bf16_f32 v80, v96, v97
	v_cvt_pk_bf16_f32 v81, v98, v99
	v_cvt_pk_bf16_f32 v82, v100, v101
	v_cvt_pk_bf16_f32 v83, v102, v103
	v_cvt_pk_bf16_f32 v84, v146, v147
	v_cvt_pk_bf16_f32 v85, v148, v149
	v_cvt_pk_bf16_f32 v86, v150, v151
	v_cvt_pk_bf16_f32 v87, v152, v153
	v_cvt_pk_bf16_f32 v88, v104, v105
	v_cvt_pk_bf16_f32 v89, v106, v107
	v_cvt_pk_bf16_f32 v90, v108, v109
	v_cvt_pk_bf16_f32 v91, v110, v111
	v_cvt_pk_bf16_f32 v92, v154, v155
	v_cvt_pk_bf16_f32 v93, v156, v157
	v_cvt_pk_bf16_f32 v94, v158, v159
	v_cvt_pk_bf16_f32 v95, v160, v161
	s_branch .LBB0_320

; #define LAS __attribute__((address_space(3)))
; #define MFMA32(a, b, c) __builtin_amdgcn_mfma_f32_32x32x16_bf16((a), (b), (c), 0, 0, 0)
; #define AT_ISSUE_K(jn) do { const int jc_ = (jn) < ntm1 ? (jn) : ntm1; const size_t ko_ = (size_t)jc_ * 8192; ks0 = *(const u32x4*)(bK1 + ko_ + koff); ks1 = *(const u32x4*)(bK2 + ko_ + koff); } while (0)
; #define AT_WRITE_K(jn) do { LAS unsigned char* n_ = lds + ((jn) & 1) * AT_KST; *(LAS u32x4*)(n_ + dK1) = ks0; *(LAS u32x4*)(n_ + dK2) = ks1; } while (0)
; #define AT_WRITE_V(jn) do { LAS unsigned char* n_ = lds + ((jn) & 1) * AT_KST; *(LAS u32x4*)(n_ + dV0) = vs0; *(LAS u32x4*)(n_ + dV1) = vs1; } while (0)
; __device__ __forceinline__ void at_pv_half(const LAS unsigned char* vp, const bf16x8 (&pf)[4], f32x16 (&O)[4], f32x16& L) {
;     bf16x8 va[8], vb[8];
; #pragma unroll
;     for (int e = 0; e < 2; ++e)
; #pragma unroll
;         for (int ks = 0; ks < 4; ++ks) va[e * 4 + ks] = *(const LAS bf16x8*)(vp + e * 32 * AT_ROWB + 32 * ks);
; #pragma unroll
;     for (int e = 0; e < 2; ++e)
; #pragma unroll
;         for (int ks = 0; ks < 4; ++ks) vb[e * 4 + ks] = *(const LAS bf16x8*)(vp + (2 + e) * 32 * AT_ROWB + 32 * ks);
;     const short one = (short)0x3F80; const bf16x8 ones = {one, one, one, one, one, one, one, one};
;     __builtin_amdgcn_sched_barrier(0);
;     __builtin_amdgcn_s_setprio(1);
; #pragma unroll
;     for (int ks = 0; ks < 4; ++ks) L = MFMA32(ones, pf[ks], L);
;     __builtin_amdgcn_sched_barrier(0);
; #pragma unroll
;     for (int ks = 0; ks < 4; ++ks) { O[0] = MFMA32(va[ks], pf[ks], O[0]); O[1] = MFMA32(va[4 + ks], pf[ks], O[1]); }
; #pragma unroll
;     for (int ks = 0; ks < 4; ++ks) { O[2] = MFMA32(vb[ks], pf[ks], O[2]); O[3] = MFMA32(vb[4 + ks], pf[ks], O[3]); }
;     __builtin_amdgcn_s_setprio(0);
; __device__ __forceinline__ void attn_item(LAS unsigned char* lds, const bf16_t* Q, const bf16_t* Kb, const bf16_t* VT, bf16_t* aout, const float* subg, float lam, float omli, float kbound, int head, int qb) {
;     ...
;             __builtin_amdgcn_s_setprio(3);
;             AT_WRITE_K(j + 1);
;             __syncthreads();
;             __builtin_amdgcn_s_setprio(0);
;             AT_ISSUE_K(j + 2);
;             if (act) at_pv_half(stg + vfo, pf, O, L);
;             AT_WRITE_V(j + 1);
;             __syncthreads();
.LBB0_320:
	s_setprio 3
	s_bitcmp1_b32 s56, 0
	s_cselect_b32 s55, 0x4800, 0
	s_waitcnt lgkmcnt(7)
	v_add_u32_e32 v96, s55, v213
	s_waitcnt vmcnt(3)
	ds_write_b128 v96, v[130:133]
	s_waitcnt vmcnt(2)
	ds_write_b128 v96, v[134:137] offset:9216
	s_waitcnt lgkmcnt(0)
	s_barrier
	s_setprio 0
	s_add_i32 s53, s53, 2
	s_min_i32 s58, s53, s41
	s_lshl_b64 s[60:61], s[58:59], 13
	v_lshl_add_u64 v[98:99], v[204:205], 0, s[60:61]
	v_lshl_add_u64 v[100:101], v[206:207], 0, s[60:61]
	global_load_dwordx4 v[130:133], v[98:99], off
	global_load_dwordx4 v[134:137], v[100:101], off
	s_andn2_b64 vcc, exec, s[0:1]
	s_cbranch_vccnz .LBB0_322
	v_add_u32_e32 v97, s54, v228
	ds_read_b128 v[98:101], v97 offset:36864
	ds_read_b128 v[150:153], v97 offset:41472
	ds_read_b128 v[166:169], v97 offset:46080
	ds_read_b128 v[234:237], v97 offset:50688
	ds_read_b128 v[102:105], v97 offset:36896
	ds_read_b128 v[154:157], v97 offset:41504
	ds_read_b128 v[170:173], v97 offset:46112
	ds_read_b128 v[238:241], v97 offset:50720
	ds_read_b128 v[106:109], v97 offset:36928
	ds_read_b128 v[158:161], v97 offset:41536
	ds_read_b128 v[176:179], v97 offset:46144
	ds_read_b128 v[242:245], v97 offset:50752
	ds_read_b128 v[146:149], v97 offset:36960
	ds_read_b128 v[162:165], v97 offset:41568
	ds_read_b128 v[230:233], v97 offset:46176
	ds_read_b128 v[246:249], v97 offset:50784
	s_setprio 1
	v_mfma_f32_16x16x32_bf16 v[64:67], v[76:79], v[80:83], v[64:67]
	v_mfma_f32_16x16x32_bf16 v[64:67], v[76:79], v[88:91], v[64:67]
	v_mfma_f32_16x16x32_bf16 v[64:67], v[76:79], v[84:87], v[64:67]
	v_mfma_f32_16x16x32_bf16 v[64:67], v[76:79], v[92:95], v[64:67]
	s_waitcnt vmcnt(3)
	ds_write_b128 v96, v[138:141] offset:36864
	s_waitcnt vmcnt(2)
	ds_write_b128 v96, v[142:145] offset:46080
	s_waitcnt lgkmcnt(15)
	v_mfma_f32_32x32x16_bf16 v[48:63], v[98:101], v[80:83], v[48:63]
	s_waitcnt lgkmcnt(15)
	v_mfma_f32_32x32x16_bf16 v[32:47], v[150:153], v[80:83], v[32:47]
	s_waitcnt lgkmcnt(15)
	v_mfma_f32_32x32x16_bf16 v[16:31], v[166:169], v[80:83], v[16:31]
	s_waitcnt lgkmcnt(14)
	v_mfma_f32_32x32x16_bf16 v[0:15], v[234:237], v[80:83], v[0:15]
	s_waitcnt lgkmcnt(13)
	v_mfma_f32_32x32x16_bf16 v[48:63], v[102:105], v[88:91], v[48:63]
	s_waitcnt lgkmcnt(12)
	v_mfma_f32_32x32x16_bf16 v[32:47], v[154:157], v[88:91], v[32:47]
	s_waitcnt lgkmcnt(11)
	v_mfma_f32_32x32x16_bf16 v[16:31], v[170:173], v[88:91], v[16:31]
	s_waitcnt lgkmcnt(10)
	v_mfma_f32_32x32x16_bf16 v[0:15], v[238:241], v[88:91], v[0:15]
	s_waitcnt lgkmcnt(9)
	v_mfma_f32_32x32x16_bf16 v[48:63], v[106:109], v[84:87], v[48:63]
	s_waitcnt lgkmcnt(8)
	v_mfma_f32_32x32x16_bf16 v[32:47], v[158:161], v[84:87], v[32:47]
	s_waitcnt lgkmcnt(7)
	v_mfma_f32_32x32x16_bf16 v[16:31], v[176:179], v[84:87], v[16:31]
	s_waitcnt lgkmcnt(6)
	v_mfma_f32_32x32x16_bf16 v[0:15], v[242:245], v[84:87], v[0:15]
	s_waitcnt lgkmcnt(5)
	v_mfma_f32_32x32x16_bf16 v[48:63], v[146:149], v[92:95], v[48:63]
	s_waitcnt lgkmcnt(4)
	v_mfma_f32_32x32x16_bf16 v[32:47], v[162:165], v[92:95], v[32:47]
	s_waitcnt lgkmcnt(3)
	v_mfma_f32_32x32x16_bf16 v[16:31], v[230:233], v[92:95], v[16:31]
	s_waitcnt lgkmcnt(2)
	v_mfma_f32_32x32x16_bf16 v[0:15], v[246:249], v[92:95], v[0:15]
	s_setprio 0
	s_branch .Lmy_wj3

; __device__ __forceinline__ void at_qk_half(const bool ONLINE, const bool act, const LAS unsigned char* kp, u32x4& pfa, u32x4& pfb, const char* pga, const char* pgb, const bf16x8 (&qf)[4], int q, int q0, int kbase, int hh, float& mrun, f32x16 (&O)[4], f32x16& L, bf16x8 (&pf)[4]) {
;     __builtin_amdgcn_s_setprio(3);
;     bf16x8 kf[8];
; #pragma unroll
;     for (int s = 0; s < 4; ++s) { kf[2 * s] = *(const LAS bf16x8*)(kp + 32 * s); kf[2 * s + 1] = *(const LAS bf16x8*)(kp + 32 * AT_ROWB + 32 * s); }
;     __builtin_amdgcn_sched_barrier(0);
;     pfa = *(const u32x4*)pga; pfb = *(const u32x4*)pgb;
;     __builtin_amdgcn_sched_barrier(0);
;     if (!act) { __builtin_amdgcn_s_setprio(0); return; }
;     f32x16 s0, s1;
; #pragma unroll
;     for (int i = 0; i < 16; ++i) { s0[i] = 0.f; s1[i] = 0.f; }
; #pragma unroll
;     for (int s = 0; s < 4; ++s) { s0 = MFMA32(kf[2 * s], qf[s], s0); s1 = MFMA32(kf[2 * s + 1], qf[s], s1); }
;     __builtin_amdgcn_s_setprio(0);
;     if (kbase + 63 > q0) {
;         const int kb = kbase + 4 * hh;
; #pragma unroll
;         for (int i = 0; i < 16; ++i) { const int kv = kb + (i & 3) + 8 * (i >> 2); if (kv > q) s0[i] = -INFINITY; if (kv + 32 > q) s1[i] = -INFINITY; }
;     }
;     if (ONLINE) {
; #pragma unroll
;         for (int i = 0; i < 16; ++i) { s0[i] -= mrun; s1[i] -= mrun; }
;         float mx = fmaxf(s0[0], s1[0]);
; #pragma unroll
;         for (int i = 1; i < 16; ++i) mx = at_max3(mx, s0[i], s1[i]);
;         mx = half_swap_max(mx);
;         if (__builtin_amdgcn_ballot_w64(mx > 8.f) != 0ull) {
;             const float d = fmaxf(mx, 0.f); const float alpha = __builtin_amdgcn_exp2f(-d); mrun += d;
; #pragma unroll
;             for (int e = 0; e < 4; ++e)
; #pragma unroll
;                 for (int i = 0; i < 16; ++i) O[e][i] *= alpha;
; __device__ __forceinline__ void attn_item(LAS unsigned char* lds, const bf16_t* Q, const bf16_t* Kb, const bf16_t* VT, bf16_t* aout, const float* subg, float lam, float omli, float kbound, int head, int qb) {
;     ...
;             __syncthreads();
;             __builtin_amdgcn_s_setprio(3);
;             { const int jc_ = (j + 2) < ntm1 ? (j + 2) : ntm1; const size_t ko_ = (size_t)jc_ * 8192; const char* pga = bK1 + ko_ + koff; const char* pgb = bK2 + ko_ + koff;
;               at_qk_half(online, kbase <= qmax, stg + kfo, ks0, ks1, pga, pgb, qf, q, q0, kbase, hh, mrun, O, L, pf); }
.Lmy_wj4:
	v_add_u32_e32 v232, s40, v212
	s_bitcmp1_b32 s39, 0
	s_cselect_b32 s42, 0x4800, 0
	s_sub_i32 s43, s1, 63
	s_waitcnt lgkmcnt(0)
	s_barrier
	s_setprio 3
	s_add_i32 s39, s39, 2
	s_min_i32 s58, s39, s22
	s_lshl_b64 s[40:41], s[58:59], 13
	v_lshl_add_u64 v[100:101], v[204:205], 0, s[40:41]
	v_lshl_add_u64 v[102:103], v[206:207], 0, s[40:41]
	s_cmp_gt_i32 s43, s21
	v_add_u32_e32 v104, s42, v230
	ds_read_b128 v[96:99], v104
	ds_read_b128 v[166:169], v104 offset:32
	ds_read_b128 v[162:165], v104 offset:64
	ds_read_b128 v[154:157], v104 offset:96
	ds_read_b128 v[178:181], v104 offset:4608
	ds_read_b128 v[170:173], v104 offset:4640
	ds_read_b128 v[174:177], v104 offset:4672
	ds_read_b128 v[158:161], v104 offset:4704
	global_load_dwordx4 v[142:145], v[100:101], off
	global_load_dwordx4 v[138:141], v[102:103], off
	s_cbranch_scc1 .LBB0_342
	s_cmp_le_i32 s1, s33
	s_cbranch_scc0 .Lmy_slow3
	s_andn2_b64 vcc, exec, s[8:9]
	s_cbranch_vccz .Lmy_slow3
	s_waitcnt lgkmcnt(7)
	v_mfma_f32_32x32x16_bf16 v[96:111], v[96:99], v[126:129], 0
	s_waitcnt lgkmcnt(6)
	v_mfma_f32_32x32x16_bf16 v[96:111], v[166:169], v[122:125], v[96:111]
	s_waitcnt lgkmcnt(5)
	v_mfma_f32_32x32x16_bf16 v[96:111], v[162:165], v[118:121], v[96:111]
	s_waitcnt lgkmcnt(4)
	v_mfma_f32_32x32x16_bf16 v[96:111], v[154:157], v[114:117], v[96:111]
	s_waitcnt lgkmcnt(3)
	v_mfma_f32_32x32x16_bf16 v[80:95], v[178:181], v[126:129], 0
	s_waitcnt lgkmcnt(2)
	v_mfma_f32_32x32x16_bf16 v[80:95], v[170:173], v[122:125], v[80:95]
	s_nop 8
	v_exp_f32_e32 v96, v96
	v_exp_f32_e32 v97, v97
	v_exp_f32_e32 v98, v98
	v_exp_f32_e32 v99, v99
	s_waitcnt lgkmcnt(1)
	v_mfma_f32_32x32x16_bf16 v[80:95], v[174:177], v[118:121], v[80:95]
	v_exp_f32_e32 v100, v100
	v_exp_f32_e32 v101, v101
	v_exp_f32_e32 v102, v102
	v_exp_f32_e32 v103, v103
	s_waitcnt lgkmcnt(0)
	v_mfma_f32_32x32x16_bf16 v[80:95], v[158:161], v[114:117], v[80:95]
	s_setprio 0
	v_exp_f32_e32 v104, v104
	v_exp_f32_e32 v105, v105
	v_exp_f32_e32 v106, v106
	v_exp_f32_e32 v107, v107
	v_exp_f32_e32 v108, v108
	v_exp_f32_e32 v109, v109
	v_exp_f32_e32 v110, v110
	v_exp_f32_e32 v111, v111
	s_nop 3
	v_exp_f32_e32 v154, v80
	v_exp_f32_e32 v155, v81
	v_exp_f32_e32 v156, v82
	v_exp_f32_e32 v157, v83
	v_exp_f32_e32 v158, v84
	v_exp_f32_e32 v159, v85
	v_exp_f32_e32 v160, v86
	v_exp_f32_e32 v161, v87
	v_exp_f32_e32 v162, v88
	v_exp_f32_e32 v163, v89
	v_exp_f32_e32 v164, v90
	v_exp_f32_e32 v165, v91
	v_exp_f32_e32 v166, v92
	v_exp_f32_e32 v167, v93
	v_exp_f32_e32 v168, v94
	v_exp_f32_e32 v169, v95
	v_cvt_pk_bf16_f32 v80, v96, v97
	v_cvt_pk_bf16_f32 v81, v98, v99
	v_cvt_pk_bf16_f32 v82, v100, v101
	v_cvt_pk_bf16_f32 v83, v102, v103
	v_cvt_pk_bf16_f32 v84, v154, v155
	v_cvt_pk_bf16_f32 v85, v156, v157
	v_cvt_pk_bf16_f32 v86, v158, v159
	v_cvt_pk_bf16_f32 v87, v160, v161
	v_cvt_pk_bf16_f32 v88, v104, v105
	v_cvt_pk_bf16_f32 v89, v106, v107
	v_cvt_pk_bf16_f32 v90, v108, v109
	v_cvt_pk_bf16_f32 v91, v110, v111
	v_cvt_pk_bf16_f32 v92, v162, v163
	v_cvt_pk_bf16_f32 v93, v164, v165
	v_cvt_pk_bf16_f32 v94, v166, v167
	v_cvt_pk_bf16_f32 v95, v168, v169
	s_branch .LBB0_342

; #define AT_WRITE_V(jn) do { LAS unsigned char* n_ = lds + ((jn) & 1) * AT_KST; *(LAS u32x4*)(n_ + dV0) = vs0; *(LAS u32x4*)(n_ + dV1) = vs1; } while (0)
; __device__ __forceinline__ void attn_item(LAS unsigned char* lds, const bf16_t* Q, const bf16_t* Kb, const bf16_t* VT, bf16_t* aout, const float* subg, float lam, float omli, float kbound, int head, int qb) {
;     ...
;             __builtin_amdgcn_s_setprio(3);
;             AT_WRITE_V(j + 1);
;             __syncthreads();
;             __builtin_amdgcn_s_setprio(0);
;         }
.LBB0_342:
	s_setprio 3
	s_waitcnt vmcnt(3)
	ds_write_b128 v232, v[146:149] offset:36864
	s_waitcnt vmcnt(2)
	ds_write_b128 v232, v[150:153] offset:46080
	s_waitcnt lgkmcnt(0)
	s_barrier
	s_setprio 0
	s_add_i32 s1, s1, 64
	s_cmp_eq_u32 s0, s38
	s_cbranch_scc1 .LBB0_345
	s_mov_b32 s39, s38
	s_branch .LBB0_333

; __device__ __forceinline__ void at_qk_half(const bool ONLINE, const bool act, const LAS unsigned char* kp, u32x4& pfa, u32x4& pfb, const char* pga, const char* pgb, const bf16x8 (&qf)[4], int q, int q0, int kbase, int hh, float& mrun, f32x16 (&O)[4], f32x16& L, bf16x8 (&pf)[4]) {
;     __builtin_amdgcn_s_setprio(3);
;     bf16x8 kf[8];
; #pragma unroll
;     for (int s = 0; s < 4; ++s) { kf[2 * s] = *(const LAS bf16x8*)(kp + 32 * s); kf[2 * s + 1] = *(const LAS bf16x8*)(kp + 32 * AT_ROWB + 32 * s); }
;     __builtin_amdgcn_sched_barrier(0);
;     pfa = *(const u32x4*)pga; pfb = *(const u32x4*)pgb;
;     __builtin_amdgcn_sched_barrier(0);
;     if (!act) { __builtin_amdgcn_s_setprio(0); return; }
;     f32x16 s0, s1;
; #pragma unroll
;     for (int i = 0; i < 16; ++i) { s0[i] = 0.f; s1[i] = 0.f; }
; #pragma unroll
;     for (int s = 0; s < 4; ++s) { s0 = MFMA32(kf[2 * s], qf[s], s0); s1 = MFMA32(kf[2 * s + 1], qf[s], s1); }
;     __builtin_amdgcn_s_setprio(0);
;     if (kbase + 63 > q0) {
;         const int kb = kbase + 4 * hh;
; #pragma unroll
;         for (int i = 0; i < 16; ++i) { const int kv = kb + (i & 3) + 8 * (i >> 2); if (kv > q) s0[i] = -INFINITY; if (kv + 32 > q) s1[i] = -INFINITY; }
;     }
;     if (ONLINE) {
; #pragma unroll
;         for (int i = 0; i < 16; ++i) { s0[i] -= mrun; s1[i] -= mrun; }
;         float mx = fmaxf(s0[0], s1[0]);
; #pragma unroll
;         for (int i = 1; i < 16; ++i) mx = at_max3(mx, s0[i], s1[i]);
;         mx = half_swap_max(mx);
;         if (__builtin_amdgcn_ballot_w64(mx > 8.f) != 0ull) {
;             const float d = fmaxf(mx, 0.f); const float alpha = __builtin_amdgcn_exp2f(-d); mrun += d;
; #pragma unroll
;             for (int e = 0; e < 4; ++e)
; __device__ __forceinline__ void attn_item(LAS unsigned char* lds, const bf16_t* Q, const bf16_t* Kb, const bf16_t* VT, bf16_t* aout, const float* subg, float lam, float omli, float kbound, int head, int qb) {
;     ...
;             const LAS unsigned char* stg = lds + (j & 1) * AT_KST; const int kbase = j * 64; const bool act = kbase <= qmax;
;             __builtin_amdgcn_s_setprio(3);
;             { const int jc_ = (j + 1) < ntm1 ? (j + 1) : ntm1; const size_t vo_ = (size_t)jc_ * 16384; const char* pga = bV0 + vo_ + voff; const char* pgb = bV1 + vo_ + voff;
;               at_qk_half(online, act, stg + kfo, vs0, vs1, pga, pgb, qf, q, q0, kbase, hh, mrun, O, L, pf); }
.LBB0_351:
	s_bitcmp1_b32 s38, 0
	s_cselect_b32 s0, 0x4800, 0
	s_add_i32 s40, s0, 0
	s_sub_i32 s41, s20, 63
	s_cmp_le_i32 s41, s21
	s_cselect_b64 s[0:1], -1, 0
	s_add_i32 s39, s38, 1
	s_min_i32 s58, s39, s22
	s_lshl_b64 s[42:43], s[58:59], 14
	s_cmp_gt_i32 s41, s21
	s_setprio 3
	v_lshl_add_u64 v[100:101], v[208:209], 0, s[42:43]
	v_lshl_add_u64 v[102:103], v[210:211], 0, s[42:43]
	v_add_u32_e32 v104, s40, v229
	ds_read_b128 v[96:99], v104
	ds_read_b128 v[158:161], v104 offset:32
	ds_read_b128 v[154:157], v104 offset:64
	ds_read_b128 v[146:149], v104 offset:96
	ds_read_b128 v[170:173], v104 offset:4608
	ds_read_b128 v[162:165], v104 offset:4640
	ds_read_b128 v[166:169], v104 offset:4672
	ds_read_b128 v[150:153], v104 offset:4704
	global_load_dwordx4 v[138:141], v[100:101], off
	global_load_dwordx4 v[142:145], v[102:103], off
	s_cbranch_scc1 .LBB0_358
	s_cmp_le_i32 s20, s33
	s_cbranch_scc0 .Lmy_slow4
	s_andn2_b64 vcc, exec, s[8:9]
	s_cbranch_vccz .Lmy_slow4
	s_waitcnt lgkmcnt(7)
	v_mfma_f32_32x32x16_bf16 v[96:111], v[96:99], v[126:129], 0
	s_waitcnt lgkmcnt(6)
	v_mfma_f32_32x32x16_bf16 v[96:111], v[158:161], v[122:125], v[96:111]
	s_waitcnt lgkmcnt(5)
	v_mfma_f32_32x32x16_bf16 v[96:111], v[154:157], v[118:121], v[96:111]
	s_waitcnt lgkmcnt(4)
	v_mfma_f32_32x32x16_bf16 v[96:111], v[146:149], v[114:117], v[96:111]
	s_waitcnt lgkmcnt(3)
	v_mfma_f32_32x32x16_bf16 v[80:95], v[170:173], v[126:129], 0
	s_waitcnt lgkmcnt(2)
	v_mfma_f32_32x32x16_bf16 v[80:95], v[162:165], v[122:125], v[80:95]
	s_nop 8
	v_exp_f32_e32 v96, v96
	v_exp_f32_e32 v97, v97
	v_exp_f32_e32 v98, v98
	v_exp_f32_e32 v99, v99
	s_waitcnt lgkmcnt(1)
	v_mfma_f32_32x32x16_bf16 v[80:95], v[166:169], v[118:121], v[80:95]
	v_exp_f32_e32 v100, v100
	v_exp_f32_e32 v101, v101
	v_exp_f32_e32 v102, v102
	v_exp_f32_e32 v103, v103
	s_waitcnt lgkmcnt(0)
	v_mfma_f32_32x32x16_bf16 v[80:95], v[150:153], v[114:117], v[80:95]
	s_setprio 0
	v_exp_f32_e32 v104, v104
	v_exp_f32_e32 v105, v105
	v_exp_f32_e32 v106, v106
	v_exp_f32_e32 v107, v107
	v_exp_f32_e32 v108, v108
	v_exp_f32_e32 v109, v109
	v_exp_f32_e32 v110, v110
	v_exp_f32_e32 v111, v111
	s_nop 3
	v_exp_f32_e32 v146, v80
	v_exp_f32_e32 v147, v81
	v_exp_f32_e32 v148, v82
	v_exp_f32_e32 v149, v83
	v_exp_f32_e32 v150, v84
	v_exp_f32_e32 v151, v85
	v_exp_f32_e32 v152, v86
	v_exp_f32_e32 v153, v87
	v_exp_f32_e32 v154, v88
	v_exp_f32_e32 v155, v89
	v_exp_f32_e32 v156, v90
	v_exp_f32_e32 v157, v91
	v_exp_f32_e32 v158, v92
	v_exp_f32_e32 v159, v93
	v_exp_f32_e32 v160, v94
	v_exp_f32_e32 v161, v95
	v_cvt_pk_bf16_f32 v80, v96, v97
	v_cvt_pk_bf16_f32 v81, v98, v99
	v_cvt_pk_bf16_f32 v82, v100, v101
	v_cvt_pk_bf16_f32 v83, v102, v103
	v_cvt_pk_bf16_f32 v84, v146, v147
	v_cvt_pk_bf16_f32 v85, v148, v149
	v_cvt_pk_bf16_f32 v86, v150, v151
	v_cvt_pk_bf16_f32 v87, v152, v153
	v_cvt_pk_bf16_f32 v88, v104, v105
	v_cvt_pk_bf16_f32 v89, v106, v107
	v_cvt_pk_bf16_f32 v90, v108, v109
	v_cvt_pk_bf16_f32 v91, v110, v111
	v_cvt_pk_bf16_f32 v92, v154, v155
	v_cvt_pk_bf16_f32 v93, v156, v157
	v_cvt_pk_bf16_f32 v94, v158, v159
	v_cvt_pk_bf16_f32 v95, v160, v161
	s_branch .LBB0_358

; #define LAS __attribute__((address_space(3)))
; #define MFMA32(a, b, c) __builtin_amdgcn_mfma_f32_32x32x16_bf16((a), (b), (c), 0, 0, 0)
; #define AT_ISSUE_K(jn) do { const int jc_ = (jn) < ntm1 ? (jn) : ntm1; const size_t ko_ = (size_t)jc_ * 8192; ks0 = *(const u32x4*)(bK1 + ko_ + koff); ks1 = *(const u32x4*)(bK2 + ko_ + koff); } while (0)
; #define AT_WRITE_K(jn) do { LAS unsigned char* n_ = lds + ((jn) & 1) * AT_KST; *(LAS u32x4*)(n_ + dK1) = ks0; *(LAS u32x4*)(n_ + dK2) = ks1; } while (0)
; #define AT_WRITE_V(jn) do { LAS unsigned char* n_ = lds + ((jn) & 1) * AT_KST; *(LAS u32x4*)(n_ + dV0) = vs0; *(LAS u32x4*)(n_ + dV1) = vs1; } while (0)
; __device__ __forceinline__ void at_pv_half(const LAS unsigned char* vp, const bf16x8 (&pf)[4], f32x16 (&O)[4], f32x16& L) {
;     bf16x8 va[8], vb[8];
; #pragma unroll
;     for (int e = 0; e < 2; ++e)
; #pragma unroll
;         for (int ks = 0; ks < 4; ++ks) va[e * 4 + ks] = *(const LAS bf16x8*)(vp + e * 32 * AT_ROWB + 32 * ks);
; #pragma unroll
;     for (int e = 0; e < 2; ++e)
; #pragma unroll
;         for (int ks = 0; ks < 4; ++ks) vb[e * 4 + ks] = *(const LAS bf16x8*)(vp + (2 + e) * 32 * AT_ROWB + 32 * ks);
;     const short one = (short)0x3F80; const bf16x8 ones = {one, one, one, one, one, one, one, one};
;     __builtin_amdgcn_sched_barrier(0);
;     __builtin_amdgcn_s_setprio(1);
; #pragma unroll
;     for (int ks = 0; ks < 4; ++ks) L = MFMA32(ones, pf[ks], L);
;     __builtin_amdgcn_sched_barrier(0);
; #pragma unroll
;     for (int ks = 0; ks < 4; ++ks) { O[0] = MFMA32(va[ks], pf[ks], O[0]); O[1] = MFMA32(va[4 + ks], pf[ks], O[1]); }
; #pragma unroll
;     for (int ks = 0; ks < 4; ++ks) { O[2] = MFMA32(vb[ks], pf[ks], O[2]); O[3] = MFMA32(vb[4 + ks], pf[ks], O[3]); }
;     __builtin_amdgcn_s_setprio(0);
; __device__ __forceinline__ void attn_item(LAS unsigned char* lds, const bf16_t* Q, const bf16_t* Kb, const bf16_t* VT, bf16_t* aout, const float* subg, float lam, float omli, float kbound, int head, int qb) {
;     ...
;             __builtin_amdgcn_s_setprio(3);
;             AT_WRITE_K(j + 1);
;             __syncthreads();
;             __builtin_amdgcn_s_setprio(0);
;             AT_ISSUE_K(j + 2);
;             if (act) at_pv_half(stg + vfo, pf, O, L);
;             AT_WRITE_V(j + 1);
;             __syncthreads();
.LBB0_358:
	s_setprio 3
	s_bitcmp1_b32 s39, 0
	s_cselect_b32 s41, 0x4800, 0
	s_waitcnt lgkmcnt(7)
	v_add_u32_e32 v96, s41, v213
	s_waitcnt vmcnt(3)
	ds_write_b128 v96, v[130:133]
	s_waitcnt vmcnt(2)
	ds_write_b128 v96, v[134:137] offset:9216
	s_waitcnt lgkmcnt(0)
	s_barrier
	s_setprio 0
	s_add_i32 s38, s38, 2
	s_min_i32 s58, s38, s22
	s_lshl_b64 s[42:43], s[58:59], 13
	v_lshl_add_u64 v[98:99], v[204:205], 0, s[42:43]
	v_lshl_add_u64 v[100:101], v[206:207], 0, s[42:43]
	global_load_dwordx4 v[130:133], v[98:99], off
	global_load_dwordx4 v[134:137], v[100:101], off
	s_andn2_b64 vcc, exec, s[0:1]
	s_cbranch_vccnz .LBB0_360
	v_add_u32_e32 v97, s40, v228
	ds_read_b128 v[98:101], v97 offset:36864
	ds_read_b128 v[150:153], v97 offset:41472
	ds_read_b128 v[166:169], v97 offset:46080
	ds_read_b128 v[230:233], v97 offset:50688
	ds_read_b128 v[102:105], v97 offset:36896
	ds_read_b128 v[154:157], v97 offset:41504
	ds_read_b128 v[170:173], v97 offset:46112
	ds_read_b128 v[234:237], v97 offset:50720
	ds_read_b128 v[106:109], v97 offset:36928
	ds_read_b128 v[158:161], v97 offset:41536
	ds_read_b128 v[176:179], v97 offset:46144
	ds_read_b128 v[238:241], v97 offset:50752
	ds_read_b128 v[146:149], v97 offset:36960
	ds_read_b128 v[162:165], v97 offset:41568
	ds_read_b128 v[184:187], v97 offset:46176
	ds_read_b128 v[242:245], v97 offset:50784
	s_setprio 1
	v_mfma_f32_16x16x32_bf16 v[64:67], v[76:79], v[80:83], v[64:67]
	v_mfma_f32_16x16x32_bf16 v[64:67], v[76:79], v[88:91], v[64:67]
	v_mfma_f32_16x16x32_bf16 v[64:67], v[76:79], v[84:87], v[64:67]
	v_mfma_f32_16x16x32_bf16 v[64:67], v[76:79], v[92:95], v[64:67]
	s_waitcnt vmcnt(3)
	ds_write_b128 v96, v[138:141] offset:36864
	s_waitcnt vmcnt(2)
	ds_write_b128 v96, v[142:145] offset:46080
	s_waitcnt lgkmcnt(15)
	v_mfma_f32_32x32x16_bf16 v[48:63], v[98:101], v[80:83], v[48:63]
	s_waitcnt lgkmcnt(15)
	v_mfma_f32_32x32x16_bf16 v[32:47], v[150:153], v[80:83], v[32:47]
	s_waitcnt lgkmcnt(15)
	v_mfma_f32_32x32x16_bf16 v[16:31], v[166:169], v[80:83], v[16:31]
	s_waitcnt lgkmcnt(14)
	v_mfma_f32_32x32x16_bf16 v[0:15], v[230:233], v[80:83], v[0:15]
	s_waitcnt lgkmcnt(13)
	v_mfma_f32_32x32x16_bf16 v[48:63], v[102:105], v[88:91], v[48:63]
	s_waitcnt lgkmcnt(12)
	v_mfma_f32_32x32x16_bf16 v[32:47], v[154:157], v[88:91], v[32:47]
	s_waitcnt lgkmcnt(11)
	v_mfma_f32_32x32x16_bf16 v[16:31], v[170:173], v[88:91], v[16:31]
	s_waitcnt lgkmcnt(10)
	v_mfma_f32_32x32x16_bf16 v[0:15], v[234:237], v[88:91], v[0:15]
	s_waitcnt lgkmcnt(9)
	v_mfma_f32_32x32x16_bf16 v[48:63], v[106:109], v[84:87], v[48:63]
	s_waitcnt lgkmcnt(8)
	v_mfma_f32_32x32x16_bf16 v[32:47], v[158:161], v[84:87], v[32:47]
	s_waitcnt lgkmcnt(7)
	v_mfma_f32_32x32x16_bf16 v[16:31], v[176:179], v[84:87], v[16:31]
	s_waitcnt lgkmcnt(6)
	v_mfma_f32_32x32x16_bf16 v[0:15], v[238:241], v[84:87], v[0:15]
	s_waitcnt lgkmcnt(5)
	v_mfma_f32_32x32x16_bf16 v[48:63], v[146:149], v[92:95], v[48:63]
	s_waitcnt lgkmcnt(4)
	v_mfma_f32_32x32x16_bf16 v[32:47], v[162:165], v[92:95], v[32:47]
	s_waitcnt lgkmcnt(3)
	v_mfma_f32_32x32x16_bf16 v[16:31], v[184:187], v[92:95], v[16:31]
	s_waitcnt lgkmcnt(2)
	v_mfma_f32_32x32x16_bf16 v[0:15], v[242:245], v[92:95], v[0:15]
	s_setprio 0
	s_branch .Lmy_wj6
